# w_out context-row fix-up loop: lines of chunks 2..4 (and the gamma pieces) requested right behind the first chunk's loads so the later dependent load rounds hit the caches
# baseline (speedup 1.0000x reference)
.LBB0_669:
	v_lshl_add_u64 v[20:21], s[62:63], 0, v[8:9]
	v_add_co_u32_e32 v10, vcc, 0x9600000, v20
	v_lshl_add_u64 v[58:59], s[10:11], 0, v[8:9]
	s_waitcnt lgkmcnt(0)
	v_addc_co_u32_e32 v11, vcc, 0, v21, vcc
	v_add_co_u32_e32 v12, vcc, 0x9a00000, v20
	global_load_dwordx4 v[26:29], v[10:11], off
	s_nop 0
	v_addc_co_u32_e32 v13, vcc, 0, v21, vcc
	v_add_co_u32_e32 v14, vcc, 0x9e00000, v20
	v_lshl_add_u64 v[22:23], s[4:5], 0, v[4:5]
	s_nop 0
	v_addc_co_u32_e32 v15, vcc, 0, v21, vcc
	v_add_co_u32_e32 v16, vcc, 0xa200000, v20
	global_load_dwordx4 v[30:33], v[12:13], off
	global_load_dwordx4 v[34:37], v[14:15], off
	v_addc_co_u32_e32 v17, vcc, 0, v21, vcc
	v_add_co_u32_e32 v18, vcc, 0xa600000, v20
	s_waitcnt vmcnt(2)
	v_pk_add_f32 v[26:27], v[26:27], 0 op_sel_hi:[1,0]
	v_addc_co_u32_e32 v19, vcc, 0, v21, vcc
	v_add_co_u32_e32 v20, vcc, 0xaa00000, v20
	global_load_dwordx4 v[38:41], v[16:17], off
	global_load_dwordx4 v[42:45], v[18:19], off
	v_addc_co_u32_e32 v21, vcc, 0, v21, vcc
	global_load_dwordx4 v[46:49], v[20:21], off
	global_load_dwordx4 v[50:53], v[58:59], off
	global_load_dwordx4 v[54:57], v[0:1], off
	global_load_dwordx4 v[74:77], v[10:11], off offset:1024
	global_load_dwordx4 v[74:77], v[12:13], off offset:1024
	global_load_dwordx4 v[74:77], v[14:15], off offset:1024
	global_load_dwordx4 v[74:77], v[16:17], off offset:1024
	global_load_dwordx4 v[74:77], v[18:19], off offset:1024
	global_load_dwordx4 v[74:77], v[20:21], off offset:1024
	global_load_dwordx4 v[74:77], v[58:59], off offset:1024
	global_load_dwordx4 v[74:77], v[0:1], off offset:1024
	global_load_dwordx4 v[74:77], v[10:11], off offset:2048
	global_load_dwordx4 v[74:77], v[12:13], off offset:2048
	global_load_dwordx4 v[74:77], v[14:15], off offset:2048
	global_load_dwordx4 v[74:77], v[16:17], off offset:2048
	global_load_dwordx4 v[74:77], v[18:19], off offset:2048
	global_load_dwordx4 v[74:77], v[20:21], off offset:2048
	global_load_dwordx4 v[74:77], v[58:59], off offset:2048
	global_load_dwordx4 v[74:77], v[0:1], off offset:2048
	global_load_dwordx4 v[74:77], v[10:11], off offset:3072
	global_load_dwordx4 v[74:77], v[12:13], off offset:3072
	global_load_dwordx4 v[74:77], v[14:15], off offset:3072
	global_load_dwordx4 v[74:77], v[16:17], off offset:3072
	global_load_dwordx4 v[74:77], v[18:19], off offset:3072
	global_load_dwordx4 v[74:77], v[20:21], off offset:3072
	global_load_dwordx4 v[74:77], v[58:59], off offset:3072
	global_load_dwordx4 v[74:77], v[0:1], off offset:3072
	global_load_dwordx4 v[74:77], v[2:3], off
	global_load_dwordx4 v[74:77], v[2:3], off offset:1024
	global_load_dwordx4 v[74:77], v[2:3], off offset:2048
	global_load_dwordx4 v[74:77], v[2:3], off offset:3072
	v_add_co_u32_e32 v60, vcc, s20, v22
	s_waitcnt vmcnt(6)
	v_pk_add_f32 v[26:27], v[26:27], v[30:31]
	v_addc_co_u32_e32 v61, vcc, 0, v23, vcc
	v_pk_add_f32 v[22:23], v[28:29], 0 op_sel_hi:[1,0]
	s_waitcnt vmcnt(5)
	v_pk_add_f32 v[26:27], v[26:27], v[34:35]
	v_pk_add_f32 v[22:23], v[22:23], v[32:33]
	s_waitcnt vmcnt(4)
	v_pk_add_f32 v[26:27], v[26:27], v[38:39]
	v_pk_add_f32 v[22:23], v[22:23], v[36:37]
	s_waitcnt vmcnt(3)
	v_pk_add_f32 v[26:27], v[26:27], v[42:43]
	v_pk_add_f32 v[22:23], v[22:23], v[40:41]
	s_waitcnt vmcnt(2)
	v_pk_add_f32 v[26:27], v[26:27], v[46:47]
	v_pk_add_f32 v[22:23], v[22:23], v[44:45]
	s_waitcnt vmcnt(0)
	v_pk_fma_f32 v[64:65], v[26:27], v[54:55], v[50:51]
	v_pk_add_f32 v[22:23], v[22:23], v[48:49]
	s_nop 0
	v_pk_fma_f32 v[62:63], v[22:23], v[56:57], v[52:53]
	v_cvt_pk_bf16_f32 v22, v64, v65
	v_cvt_pk_bf16_f32 v23, v62, v63
	global_store_dwordx2 v[60:61], v[22:23], off
	global_load_dwordx4 v[26:29], v[2:3], off
	v_lshl_add_u64 v[22:23], s[4:5], 0, v[6:7]
	s_waitcnt vmcnt(0)
	v_pk_mul_f32 v[28:29], v[62:63], v[28:29]
	v_pk_mul_f32 v[26:27], v[64:65], v[26:27]
	s_nop 0
	v_cvt_pk_bf16_f32 v26, v26, v27
	v_cvt_pk_bf16_f32 v27, v28, v29
	global_store_dwordx2 v[22:23], v[26:27], off
	global_load_dwordx4 v[26:29], v[10:11], off offset:1024
	s_nop 0
	global_load_dwordx4 v[30:33], v[12:13], off offset:1024
	global_load_dwordx4 v[34:37], v[14:15], off offset:1024
	global_load_dwordx4 v[38:41], v[16:17], off offset:1024
	global_load_dwordx4 v[42:45], v[18:19], off offset:1024
	global_load_dwordx4 v[46:49], v[20:21], off offset:1024
	global_load_dwordx4 v[50:53], v[58:59], off offset:1024
	global_load_dwordx4 v[54:57], v[0:1], off offset:1024
	s_waitcnt vmcnt(7)
	v_pk_add_f32 v[28:29], v[28:29], 0 op_sel_hi:[1,0]
	v_pk_add_f32 v[26:27], v[26:27], 0 op_sel_hi:[1,0]
	s_waitcnt vmcnt(6)
	v_pk_add_f32 v[28:29], v[28:29], v[32:33]
	v_pk_add_f32 v[26:27], v[26:27], v[30:31]
	s_waitcnt vmcnt(5)
	v_pk_add_f32 v[28:29], v[28:29], v[36:37]
	v_pk_add_f32 v[26:27], v[26:27], v[34:35]
	s_waitcnt vmcnt(4)
	v_pk_add_f32 v[28:29], v[28:29], v[40:41]
	v_pk_add_f32 v[26:27], v[26:27], v[38:39]
	s_waitcnt vmcnt(3)
	v_pk_add_f32 v[28:29], v[28:29], v[44:45]
	v_pk_add_f32 v[26:27], v[26:27], v[42:43]
	s_waitcnt vmcnt(2)
	v_pk_add_f32 v[28:29], v[28:29], v[48:49]
	v_pk_add_f32 v[26:27], v[26:27], v[46:47]
	s_waitcnt vmcnt(0)
	v_pk_fma_f32 v[66:67], v[28:29], v[56:57], v[52:53]
	v_pk_fma_f32 v[68:69], v[26:27], v[54:55], v[50:51]
	v_cvt_pk_bf16_f32 v27, v66, v67
	v_cvt_pk_bf16_f32 v26, v68, v69
	global_store_dwordx2 v[60:61], v[26:27], off offset:512
	global_load_dwordx4 v[26:29], v[2:3], off offset:1024
	s_waitcnt vmcnt(0)
	v_pk_mul_f32 v[28:29], v[66:67], v[28:29]
	v_pk_mul_f32 v[26:27], v[68:69], v[26:27]
	s_nop 0
	v_cvt_pk_bf16_f32 v26, v26, v27
	v_cvt_pk_bf16_f32 v27, v28, v29
	global_store_dwordx2 v[22:23], v[26:27], off offset:512
	global_load_dwordx4 v[26:29], v[10:11], off offset:2048
	s_nop 0
	global_load_dwordx4 v[30:33], v[12:13], off offset:2048
	global_load_dwordx4 v[34:37], v[14:15], off offset:2048
	global_load_dwordx4 v[38:41], v[16:17], off offset:2048
	global_load_dwordx4 v[42:45], v[18:19], off offset:2048
	global_load_dwordx4 v[46:49], v[20:21], off offset:2048
	global_load_dwordx4 v[50:53], v[58:59], off offset:2048
	global_load_dwordx4 v[54:57], v[0:1], off offset:2048
	s_waitcnt vmcnt(7)
	v_pk_add_f32 v[28:29], v[28:29], 0 op_sel_hi:[1,0]
	v_pk_add_f32 v[26:27], v[26:27], 0 op_sel_hi:[1,0]
	s_waitcnt vmcnt(6)
	v_pk_add_f32 v[28:29], v[28:29], v[32:33]
	v_pk_add_f32 v[26:27], v[26:27], v[30:31]
	s_waitcnt vmcnt(5)
	v_pk_add_f32 v[28:29], v[28:29], v[36:37]
	v_pk_add_f32 v[26:27], v[26:27], v[34:35]
	s_waitcnt vmcnt(4)
	v_pk_add_f32 v[28:29], v[28:29], v[40:41]
	v_pk_add_f32 v[26:27], v[26:27], v[38:39]
	s_waitcnt vmcnt(3)
	v_pk_add_f32 v[28:29], v[28:29], v[44:45]
	v_pk_add_f32 v[26:27], v[26:27], v[42:43]
	s_waitcnt vmcnt(2)
	v_pk_add_f32 v[28:29], v[28:29], v[48:49]
	v_pk_add_f32 v[26:27], v[26:27], v[46:47]
	s_waitcnt vmcnt(0)
	v_pk_fma_f32 v[70:71], v[28:29], v[56:57], v[52:53]
	v_pk_fma_f32 v[72:73], v[26:27], v[54:55], v[50:51]
	v_cvt_pk_bf16_f32 v27, v70, v71
	v_cvt_pk_bf16_f32 v26, v72, v73
	global_store_dwordx2 v[60:61], v[26:27], off offset:1024
	global_load_dwordx4 v[26:29], v[2:3], off offset:2048
	s_waitcnt vmcnt(0)
	v_pk_mul_f32 v[28:29], v[70:71], v[28:29]
	v_pk_mul_f32 v[26:27], v[72:73], v[26:27]
	s_nop 0
	v_cvt_pk_bf16_f32 v26, v26, v27
	v_cvt_pk_bf16_f32 v27, v28, v29
	global_store_dwordx2 v[22:23], v[26:27], off offset:1024
	global_load_dwordx4 v[26:29], v[10:11], off offset:3072
	s_nop 0
	global_load_dwordx4 v[30:33], v[12:13], off offset:3072
	global_load_dwordx4 v[34:37], v[14:15], off offset:3072
	global_load_dwordx4 v[38:41], v[16:17], off offset:3072
	global_load_dwordx4 v[42:45], v[18:19], off offset:3072
	global_load_dwordx4 v[46:49], v[20:21], off offset:3072
	global_load_dwordx4 v[50:53], v[58:59], off offset:3072
	global_load_dwordx4 v[54:57], v[0:1], off offset:3072
	v_mul_f32_e32 v20, v67, v67
	v_fmac_f32_e32 v20, v66, v66
	s_waitcnt vmcnt(7)
	v_pk_add_f32 v[10:11], v[28:29], 0 op_sel_hi:[1,0]
	v_pk_add_f32 v[12:13], v[26:27], 0 op_sel_hi:[1,0]
	s_waitcnt vmcnt(6)
	v_pk_add_f32 v[10:11], v[10:11], v[32:33]
	v_pk_add_f32 v[12:13], v[12:13], v[30:31]
	s_waitcnt vmcnt(5)
	v_pk_add_f32 v[10:11], v[10:11], v[36:37]
	v_pk_add_f32 v[12:13], v[12:13], v[34:35]
	s_waitcnt vmcnt(4)
	v_pk_add_f32 v[10:11], v[10:11], v[40:41]
	v_pk_add_f32 v[12:13], v[12:13], v[38:39]
	s_waitcnt vmcnt(3)
	v_pk_add_f32 v[10:11], v[10:11], v[44:45]
	v_pk_add_f32 v[12:13], v[12:13], v[42:43]
	s_waitcnt vmcnt(2)
	v_pk_add_f32 v[10:11], v[10:11], v[48:49]
	v_pk_add_f32 v[12:13], v[12:13], v[46:47]
	s_waitcnt vmcnt(0)
	v_pk_fma_f32 v[16:17], v[10:11], v[56:57], v[52:53]
	v_pk_fma_f32 v[18:19], v[12:13], v[54:55], v[50:51]
	v_cvt_pk_bf16_f32 v11, v16, v17
	v_cvt_pk_bf16_f32 v10, v18, v19
	global_store_dwordx2 v[60:61], v[10:11], off offset:1536
	global_load_dwordx4 v[12:15], v[2:3], off offset:3072
	v_mul_f32_e32 v10, v65, v65
	v_mul_f32_e32 v11, v63, v63
	v_fmac_f32_e32 v10, v64, v64
	v_fmac_f32_e32 v11, v62, v62
	v_add_f32_e32 v10, v10, v11
	v_mul_f32_e32 v11, v69, v69
	v_fmac_f32_e32 v11, v68, v68
	v_add_f32_e32 v11, v11, v20
	v_add_f32_e32 v10, v10, v11
	v_mul_f32_e32 v11, v73, v73
	v_mul_f32_e32 v20, v71, v71
	v_fmac_f32_e32 v11, v72, v72
	v_fmac_f32_e32 v20, v70, v70
	v_add_f32_e32 v11, v11, v20
	v_add_f32_e32 v10, v10, v11
	v_mul_f32_e32 v11, v19, v19
	v_mul_f32_e32 v20, v17, v17
	v_fmac_f32_e32 v11, v18, v18
	v_fmac_f32_e32 v20, v16, v16
	v_add_f32_e32 v11, v11, v20
	v_add_f32_e32 v10, v10, v11
	ds_swizzle_b32 v11, v10 offset:swizzle(SWAP,1)
	s_waitcnt lgkmcnt(0)
	v_add_f32_e32 v10, v10, v11
	ds_swizzle_b32 v11, v10 offset:swizzle(SWAP,2)
	s_waitcnt lgkmcnt(0)
	v_add_f32_e32 v10, v10, v11
	ds_swizzle_b32 v11, v10 offset:swizzle(SWAP,4)
	s_waitcnt lgkmcnt(0)
	v_add_f32_e32 v10, v10, v11
	ds_swizzle_b32 v11, v10 offset:swizzle(SWAP,8)
	s_waitcnt lgkmcnt(0)
	v_add_f32_e32 v10, v10, v11
	ds_swizzle_b32 v11, v10 offset:swizzle(SWAP,16)
	s_waitcnt lgkmcnt(0)
	v_add_f32_e32 v10, v10, v11
	ds_bpermute_b32 v11, v24, v10
	s_waitcnt vmcnt(0)
	v_pk_mul_f32 v[14:15], v[16:17], v[14:15]
	v_pk_mul_f32 v[12:13], v[18:19], v[12:13]
	s_nop 0
	v_cvt_pk_bf16_f32 v12, v12, v13
	v_cvt_pk_bf16_f32 v13, v14, v15
	global_store_dwordx2 v[22:23], v[12:13], off offset:1536
	s_and_saveexec_b64 s[18:19], s[6:7]
	s_cbranch_execz .LBB0_668
	s_add_u32 s22, s4, s1
	s_waitcnt lgkmcnt(0)
	v_add_f32_e32 v10, v10, v11
	s_addc_u32 s23, s5, s2
	global_store_dword v25, v10, s[22:23]
	s_branch .LBB0_668
